# B-layer score-loop batching only at the first memory-attention site
# speedup vs baseline: 1.0049x; 1.0049x over previous
.LBB0_89:
	s_or_b64 exec, exec, s[4:5]
	v_and_b32_e32 v5, 64, v229
	v_mov_b32_e32 v1, v4
	v_xor_b32_e32 v4, 16, v229
	v_add_u32_e32 v5, 64, v5
	v_cmp_lt_i32_e32 vcc, v4, v5
	v_and_b32_e32 v71, 15, v52
	v_mad_u32_u24 v79, v71, s14, v72
	v_cndmask_b32_e32 v78, v229, v4, vcc
	v_xor_b32_e32 v4, 32, v229
	v_cmp_lt_i32_e32 vcc, v4, v5
	v_mov_b32_e32 v65, v6
	v_cndmask_b32_e32 v73, v229, v4, vcc
	v_lshlrev_b32_e32 v73, 2, v73
	ds_read_b128 v[116:119], v79
	ds_read_b128 v[120:123], v79 offset:64
	ds_read_b128 v[124:127], v79 offset:2304
	ds_read_b128 v[128:131], v79 offset:2368
	ds_read_b128 v[132:135], v79 offset:4608
	ds_read_b128 v[136:139], v79 offset:4672
	ds_read_b128 v[140:143], v79 offset:6912
	ds_read_b128 v[144:147], v79 offset:6976
	ds_read_b128 v[148:151], v79 offset:9216
	ds_read_b128 v[152:155], v79 offset:9280
	ds_read_b128 v[156:159], v79 offset:11520
	ds_read_b128 v[160:163], v79 offset:11584
	s_waitcnt lgkmcnt(6)
	v_mfma_f32_16x16x32_bf16 v[60:63], v[116:119], v[0:3], 0
	v_mfma_f32_16x16x32_bf16 v[56:59], v[124:127], v[0:3], 0
	v_mfma_f32_16x16x32_bf16 v[52:55], v[132:135], v[0:3], 0
	v_mfma_f32_16x16x32_bf16 v[60:63], v[120:123], v[64:67], v[60:63]
	v_mfma_f32_16x16x32_bf16 v[56:59], v[128:131], v[64:67], v[56:59]
	v_mfma_f32_16x16x32_bf16 v[52:55], v[136:139], v[64:67], v[52:55]
	ds_read_b128 v[116:119], v79 offset:13824
	ds_read_b128 v[120:123], v79 offset:13888
	ds_read_b128 v[124:127], v79 offset:16128
	ds_read_b128 v[128:131], v79 offset:16192
	ds_read_b128 v[132:135], v79 offset:18432
	ds_read_b128 v[136:139], v79 offset:18496
	s_waitcnt lgkmcnt(6)
	v_mfma_f32_16x16x32_bf16 v[48:51], v[140:143], v[0:3], 0
	v_mfma_f32_16x16x32_bf16 v[44:47], v[148:151], v[0:3], 0
	v_mfma_f32_16x16x32_bf16 v[40:43], v[156:159], v[0:3], 0
	v_mfma_f32_16x16x32_bf16 v[48:51], v[144:147], v[64:67], v[48:51]
	v_mfma_f32_16x16x32_bf16 v[44:47], v[152:155], v[64:67], v[44:47]
	v_mfma_f32_16x16x32_bf16 v[40:43], v[160:163], v[64:67], v[40:43]
	ds_read_b128 v[140:143], v79 offset:20736
	ds_read_b128 v[144:147], v79 offset:20800
	ds_read_b128 v[148:151], v79 offset:23040
	ds_read_b128 v[152:155], v79 offset:23104
	ds_read_b128 v[156:159], v79 offset:25344
	ds_read_b128 v[160:163], v79 offset:25408
	s_waitcnt lgkmcnt(6)
	v_mfma_f32_16x16x32_bf16 v[36:39], v[116:119], v[0:3], 0
	v_mfma_f32_16x16x32_bf16 v[32:35], v[124:127], v[0:3], 0
	v_mfma_f32_16x16x32_bf16 v[28:31], v[132:135], v[0:3], 0
	v_mfma_f32_16x16x32_bf16 v[36:39], v[120:123], v[64:67], v[36:39]
	v_mfma_f32_16x16x32_bf16 v[32:35], v[128:131], v[64:67], v[32:35]
	v_mfma_f32_16x16x32_bf16 v[28:31], v[136:139], v[64:67], v[28:31]
	ds_read_b128 v[116:119], v79 offset:27648
	ds_read_b128 v[120:123], v79 offset:27712
	ds_read_b128 v[124:127], v79 offset:29952
	ds_read_b128 v[128:131], v79 offset:30016
	ds_read_b128 v[132:135], v79 offset:32256
	ds_read_b128 v[136:139], v79 offset:32320
	s_waitcnt lgkmcnt(6)
	v_mfma_f32_16x16x32_bf16 v[24:27], v[140:143], v[0:3], 0
	v_mfma_f32_16x16x32_bf16 v[20:23], v[148:151], v[0:3], 0
	v_mfma_f32_16x16x32_bf16 v[16:19], v[156:159], v[0:3], 0
	v_mfma_f32_16x16x32_bf16 v[24:27], v[144:147], v[64:67], v[24:27]
	v_mfma_f32_16x16x32_bf16 v[20:23], v[152:155], v[64:67], v[20:23]
	v_mfma_f32_16x16x32_bf16 v[16:19], v[160:163], v[64:67], v[16:19]
	s_waitcnt lgkmcnt(0)
	v_mfma_f32_16x16x32_bf16 v[12:15], v[116:119], v[0:3], 0
	v_mfma_f32_16x16x32_bf16 v[8:11], v[124:127], v[0:3], 0
	v_mfma_f32_16x16x32_bf16 v[4:7], v[132:135], v[0:3], 0
	v_mfma_f32_16x16x32_bf16 v[12:15], v[120:123], v[64:67], v[12:15]
	v_mfma_f32_16x16x32_bf16 v[8:11], v[128:131], v[64:67], v[8:11]
	v_mfma_f32_16x16x32_bf16 v[4:7], v[136:139], v[64:67], v[4:7]
	ds_read_b128 v[116:119], v79 offset:34560
	ds_read_b128 v[120:123], v79 offset:34624
	s_waitcnt lgkmcnt(0)
	v_mfma_f32_16x16x32_bf16 v[124:127], v[116:119], v[0:3], 0
	v_mfma_f32_16x16x32_bf16 v[0:3], v[120:123], v[64:67], v[124:127]
	v_mul_f32_e32 v64, 0x3e000000, v60
	v_mul_f32_e32 v65, 0x3e000000, v61
	s_mov_b32 s2, 0xff61b1e6
	v_max3_f32 v64, v64, s2, v65
	v_mul_f32_e32 v65, 0x3e000000, v62
	v_mul_f32_e32 v66, 0x3e000000, v63
	v_max3_f32 v64, v64, v65, v66
	v_mul_f32_e32 v65, 0x3e000000, v56
	v_mul_f32_e32 v66, 0x3e000000, v57
	v_max3_f32 v64, v64, v65, v66
	v_mul_f32_e32 v65, 0x3e000000, v58
	v_mul_f32_e32 v66, 0x3e000000, v59
	v_max3_f32 v64, v64, v65, v66
	v_mul_f32_e32 v65, 0x3e000000, v52
	v_mul_f32_e32 v66, 0x3e000000, v53
	v_max3_f32 v64, v64, v65, v66
	v_mul_f32_e32 v65, 0x3e000000, v54
	v_mul_f32_e32 v66, 0x3e000000, v55
	v_max3_f32 v64, v64, v65, v66
	v_mul_f32_e32 v65, 0x3e000000, v48
	v_mul_f32_e32 v66, 0x3e000000, v49
	v_max3_f32 v64, v64, v65, v66
	v_mul_f32_e32 v65, 0x3e000000, v50
	v_mul_f32_e32 v66, 0x3e000000, v51
	v_max3_f32 v64, v64, v65, v66
	v_mul_f32_e32 v65, 0x3e000000, v44
	v_mul_f32_e32 v66, 0x3e000000, v45
	v_max3_f32 v64, v64, v65, v66
	v_mul_f32_e32 v65, 0x3e000000, v46
	v_mul_f32_e32 v66, 0x3e000000, v47
	v_max3_f32 v64, v64, v65, v66
	v_mul_f32_e32 v65, 0x3e000000, v40
	v_mul_f32_e32 v66, 0x3e000000, v41
	v_max3_f32 v64, v64, v65, v66
	v_mul_f32_e32 v65, 0x3e000000, v42
	v_mul_f32_e32 v66, 0x3e000000, v43
	v_max3_f32 v64, v64, v65, v66
	v_mul_f32_e32 v65, 0x3e000000, v36
	v_mul_f32_e32 v66, 0x3e000000, v37
	v_max3_f32 v64, v64, v65, v66
	v_mul_f32_e32 v65, 0x3e000000, v38
	v_mul_f32_e32 v66, 0x3e000000, v39
	v_max3_f32 v64, v64, v65, v66
	v_mul_f32_e32 v65, 0x3e000000, v32
	v_mul_f32_e32 v66, 0x3e000000, v33
	v_max3_f32 v64, v64, v65, v66
	v_mul_f32_e32 v65, 0x3e000000, v34
	v_mul_f32_e32 v66, 0x3e000000, v35
	v_max3_f32 v64, v64, v65, v66
	v_mul_f32_e32 v65, 0x3e000000, v28
	v_mul_f32_e32 v66, 0x3e000000, v29
	v_max3_f32 v64, v64, v65, v66
	v_mul_f32_e32 v65, 0x3e000000, v30
	v_mul_f32_e32 v66, 0x3e000000, v31
	v_max3_f32 v64, v64, v65, v66
	v_mul_f32_e32 v65, 0x3e000000, v24
	v_mul_f32_e32 v66, 0x3e000000, v25
	v_max3_f32 v64, v64, v65, v66
	v_mul_f32_e32 v65, 0x3e000000, v26
	v_mul_f32_e32 v66, 0x3e000000, v27
	v_max3_f32 v64, v64, v65, v66
	v_mul_f32_e32 v65, 0x3e000000, v20
	v_mul_f32_e32 v66, 0x3e000000, v21
	v_max3_f32 v64, v64, v65, v66
	v_mul_f32_e32 v65, 0x3e000000, v22
	v_mul_f32_e32 v66, 0x3e000000, v23
	v_max3_f32 v64, v64, v65, v66
	v_mul_f32_e32 v65, 0x3e000000, v16
	v_mul_f32_e32 v66, 0x3e000000, v17
	v_max3_f32 v64, v64, v65, v66
	v_mul_f32_e32 v65, 0x3e000000, v18
	v_mul_f32_e32 v66, 0x3e000000, v19
	v_max3_f32 v64, v64, v65, v66
	v_mul_f32_e32 v65, 0x3e000000, v12
	v_mul_f32_e32 v66, 0x3e000000, v13
	v_max3_f32 v64, v64, v65, v66
	v_mul_f32_e32 v65, 0x3e000000, v14
	v_mul_f32_e32 v66, 0x3e000000, v15
	v_max3_f32 v64, v64, v65, v66
	v_mul_f32_e32 v65, 0x3e000000, v8
	v_mul_f32_e32 v66, 0x3e000000, v9
	v_max3_f32 v64, v64, v65, v66
	v_mul_f32_e32 v65, 0x3e000000, v10
	v_mul_f32_e32 v66, 0x3e000000, v11
	v_max3_f32 v64, v64, v65, v66
	v_mul_f32_e32 v65, 0x3e000000, v4
	v_mul_f32_e32 v66, 0x3e000000, v5
	v_max3_f32 v64, v64, v65, v66
	v_mul_f32_e32 v65, 0x3e000000, v6
	v_mul_f32_e32 v66, 0x3e000000, v7
	v_max3_f32 v64, v64, v65, v66
	v_mul_f32_e32 v65, 0x3e000000, v0
	v_mul_f32_e32 v66, 0x3e000000, v1
	v_max3_f32 v64, v64, v65, v66
	v_mul_f32_e32 v65, 0x3e000000, v2
	v_mul_f32_e32 v66, 0x3e000000, v3
	v_max3_f32 v64, v64, v65, v66
	v_lshlrev_b32_e32 v74, 2, v78
	ds_bpermute_b32 v65, v74, v64
	s_mov_b32 s2, 0x3e000000
	v_sub_u32_e32 v72, v72, v70
	s_waitcnt lgkmcnt(0)
	v_max_f32_e32 v65, v65, v65
	v_max_f32_e32 v64, v64, v65
	ds_bpermute_b32 v65, v73, v64
	s_waitcnt lgkmcnt(0)
	v_max_f32_e32 v65, v65, v65
	v_max_f32_e32 v75, v64, v65
	v_fma_f32 v60, v60, s2, -v75
	v_fma_f32 v61, v61, s2, -v75
	v_mul_f32_e32 v60, 0x3fb8aa3b, v60
	v_mul_f32_e32 v61, 0x3fb8aa3b, v61
	v_exp_f32_e32 v60, v60
	v_exp_f32_e32 v64, v61
	v_fma_f32 v61, v62, s2, -v75
	v_mul_f32_e32 v61, 0x3fb8aa3b, v61
	v_exp_f32_e32 v61, v61
	v_add_f32_e32 v65, 0, v60
	v_fma_f32 v63, v63, s2, -v75
	v_add_f32_e32 v65, v64, v65
	v_mul_f32_e32 v63, 0x3fb8aa3b, v63
	v_add_f32_e32 v62, v61, v65
	v_exp_f32_e32 v65, v63
	v_fma_f32 v56, v56, s2, -v75
	v_mul_f32_e32 v56, 0x3fb8aa3b, v56
	v_fma_f32 v57, v57, s2, -v75
	v_add_f32_e32 v63, v65, v62
	v_exp_f32_e32 v62, v56
	v_mul_f32_e32 v57, 0x3fb8aa3b, v57
	v_exp_f32_e32 v66, v57
	v_fma_f32 v57, v58, s2, -v75
	v_mul_f32_e32 v57, 0x3fb8aa3b, v57
	v_add_f32_e32 v56, v62, v63
	v_exp_f32_e32 v63, v57
	v_fma_f32 v57, v59, s2, -v75
	v_mul_f32_e32 v57, 0x3fb8aa3b, v57
	v_fma_f32 v52, v52, s2, -v75
	v_exp_f32_e32 v67, v57
	v_mul_f32_e32 v52, 0x3fb8aa3b, v52
	v_exp_f32_e32 v52, v52
	v_add_f32_e32 v56, v66, v56
	v_add_f32_e32 v56, v63, v56
	v_fma_f32 v53, v53, s2, -v75
	v_add_f32_e32 v56, v67, v56
	v_mul_f32_e32 v53, 0x3fb8aa3b, v53
	v_add_f32_e32 v57, v52, v56
	v_exp_f32_e32 v56, v53
	v_fma_f32 v53, v54, s2, -v75
	v_mul_f32_e32 v53, 0x3fb8aa3b, v53
	v_exp_f32_e32 v53, v53
	v_fma_f32 v55, v55, s2, -v75
	v_add_f32_e32 v57, v56, v57
	v_mul_f32_e32 v55, 0x3fb8aa3b, v55
	v_add_f32_e32 v54, v53, v57
	v_exp_f32_e32 v57, v55
	v_fma_f32 v48, v48, s2, -v75
	v_mul_f32_e32 v48, 0x3fb8aa3b, v48
	v_fma_f32 v49, v49, s2, -v75
	v_add_f32_e32 v55, v57, v54
	v_exp_f32_e32 v54, v48
	v_mul_f32_e32 v49, 0x3fb8aa3b, v49
	v_exp_f32_e32 v58, v49
	v_fma_f32 v49, v50, s2, -v75
	v_mul_f32_e32 v49, 0x3fb8aa3b, v49
	v_add_f32_e32 v48, v54, v55
	v_exp_f32_e32 v55, v49
	v_fma_f32 v49, v51, s2, -v75
	v_mul_f32_e32 v49, 0x3fb8aa3b, v49
	v_fma_f32 v44, v44, s2, -v75
	v_exp_f32_e32 v59, v49
	v_mul_f32_e32 v44, 0x3fb8aa3b, v44
	v_exp_f32_e32 v44, v44
	v_add_f32_e32 v48, v58, v48
	v_add_f32_e32 v48, v55, v48
	v_fma_f32 v45, v45, s2, -v75
	v_add_f32_e32 v48, v59, v48
	v_mul_f32_e32 v45, 0x3fb8aa3b, v45
	v_add_f32_e32 v49, v44, v48
	v_exp_f32_e32 v48, v45
	v_fma_f32 v45, v46, s2, -v75
	v_mul_f32_e32 v45, 0x3fb8aa3b, v45
	v_exp_f32_e32 v45, v45
	v_fma_f32 v47, v47, s2, -v75
	v_add_f32_e32 v49, v48, v49
	v_mul_f32_e32 v47, 0x3fb8aa3b, v47
	v_add_f32_e32 v46, v45, v49
	v_exp_f32_e32 v49, v47
	v_fma_f32 v40, v40, s2, -v75
	v_mul_f32_e32 v40, 0x3fb8aa3b, v40
	v_fma_f32 v41, v41, s2, -v75
	v_add_f32_e32 v47, v49, v46
	v_exp_f32_e32 v46, v40
	v_mul_f32_e32 v41, 0x3fb8aa3b, v41
	v_exp_f32_e32 v50, v41
	v_fma_f32 v41, v42, s2, -v75
	v_mul_f32_e32 v41, 0x3fb8aa3b, v41
	v_add_f32_e32 v40, v46, v47
	v_exp_f32_e32 v47, v41
	v_fma_f32 v41, v43, s2, -v75
	v_mul_f32_e32 v41, 0x3fb8aa3b, v41
	v_fma_f32 v36, v36, s2, -v75
	v_exp_f32_e32 v51, v41
	v_mul_f32_e32 v36, 0x3fb8aa3b, v36
	v_exp_f32_e32 v36, v36
	v_add_f32_e32 v40, v50, v40
	v_add_f32_e32 v40, v47, v40
	v_fma_f32 v37, v37, s2, -v75
	v_add_f32_e32 v40, v51, v40
	v_mul_f32_e32 v37, 0x3fb8aa3b, v37
	v_add_f32_e32 v41, v36, v40
	v_exp_f32_e32 v40, v37
	v_fma_f32 v37, v38, s2, -v75
	v_mul_f32_e32 v37, 0x3fb8aa3b, v37
	v_exp_f32_e32 v37, v37
	v_fma_f32 v39, v39, s2, -v75
	v_add_f32_e32 v41, v40, v41
	v_mul_f32_e32 v39, 0x3fb8aa3b, v39
	v_add_f32_e32 v38, v37, v41
	v_exp_f32_e32 v41, v39
	v_fma_f32 v32, v32, s2, -v75
	v_mul_f32_e32 v32, 0x3fb8aa3b, v32
	v_fma_f32 v33, v33, s2, -v75
	v_add_f32_e32 v39, v41, v38
	v_exp_f32_e32 v38, v32
	v_mul_f32_e32 v33, 0x3fb8aa3b, v33
	v_exp_f32_e32 v42, v33
	v_fma_f32 v33, v34, s2, -v75
	v_mul_f32_e32 v33, 0x3fb8aa3b, v33
	v_add_f32_e32 v32, v38, v39
	v_exp_f32_e32 v39, v33
	v_fma_f32 v33, v35, s2, -v75
	v_mul_f32_e32 v33, 0x3fb8aa3b, v33
	v_fma_f32 v28, v28, s2, -v75
	v_exp_f32_e32 v43, v33
	v_mul_f32_e32 v28, 0x3fb8aa3b, v28
	v_exp_f32_e32 v28, v28
	v_add_f32_e32 v32, v42, v32
	v_add_f32_e32 v32, v39, v32
	v_fma_f32 v29, v29, s2, -v75
	v_add_f32_e32 v32, v43, v32
	v_mul_f32_e32 v29, 0x3fb8aa3b, v29
	v_add_f32_e32 v33, v28, v32
	v_exp_f32_e32 v32, v29
	v_fma_f32 v29, v30, s2, -v75
	v_mul_f32_e32 v29, 0x3fb8aa3b, v29
	v_exp_f32_e32 v29, v29
	v_fma_f32 v31, v31, s2, -v75
	v_add_f32_e32 v33, v32, v33
	v_mul_f32_e32 v31, 0x3fb8aa3b, v31
	v_add_f32_e32 v30, v29, v33
	v_exp_f32_e32 v33, v31
	v_fma_f32 v24, v24, s2, -v75
	v_mul_f32_e32 v24, 0x3fb8aa3b, v24
	v_fma_f32 v25, v25, s2, -v75
	v_add_f32_e32 v31, v33, v30
	v_exp_f32_e32 v30, v24
	v_mul_f32_e32 v25, 0x3fb8aa3b, v25
	v_exp_f32_e32 v34, v25
	v_fma_f32 v25, v26, s2, -v75
	v_mul_f32_e32 v25, 0x3fb8aa3b, v25
	v_add_f32_e32 v24, v30, v31
	v_exp_f32_e32 v31, v25
	v_fma_f32 v25, v27, s2, -v75
	v_mul_f32_e32 v25, 0x3fb8aa3b, v25
	v_fma_f32 v20, v20, s2, -v75
	v_exp_f32_e32 v35, v25
	v_mul_f32_e32 v20, 0x3fb8aa3b, v20
	v_exp_f32_e32 v20, v20
	v_add_f32_e32 v24, v34, v24
	v_add_f32_e32 v24, v31, v24
	v_fma_f32 v21, v21, s2, -v75
	v_add_f32_e32 v24, v35, v24
	v_mul_f32_e32 v21, 0x3fb8aa3b, v21
	v_add_f32_e32 v25, v20, v24
	v_exp_f32_e32 v24, v21
	v_fma_f32 v21, v22, s2, -v75
	v_mul_f32_e32 v21, 0x3fb8aa3b, v21
	v_exp_f32_e32 v21, v21
	v_fma_f32 v23, v23, s2, -v75
	v_add_f32_e32 v25, v24, v25
	v_mul_f32_e32 v23, 0x3fb8aa3b, v23
	v_add_f32_e32 v22, v21, v25
	v_exp_f32_e32 v25, v23
	v_fma_f32 v16, v16, s2, -v75
	v_mul_f32_e32 v16, 0x3fb8aa3b, v16
	v_fma_f32 v17, v17, s2, -v75
	v_add_f32_e32 v23, v25, v22
	v_exp_f32_e32 v22, v16
	v_mul_f32_e32 v17, 0x3fb8aa3b, v17
	v_exp_f32_e32 v26, v17
	v_fma_f32 v17, v18, s2, -v75
	v_mul_f32_e32 v17, 0x3fb8aa3b, v17
	v_add_f32_e32 v16, v22, v23
	v_exp_f32_e32 v23, v17
	v_fma_f32 v17, v19, s2, -v75
	v_mul_f32_e32 v17, 0x3fb8aa3b, v17
	v_fma_f32 v12, v12, s2, -v75
	v_exp_f32_e32 v27, v17
	v_mul_f32_e32 v12, 0x3fb8aa3b, v12
	v_exp_f32_e32 v12, v12
	v_add_f32_e32 v16, v26, v16
	v_add_f32_e32 v16, v23, v16
	v_fma_f32 v13, v13, s2, -v75
	v_add_f32_e32 v16, v27, v16
	v_mul_f32_e32 v13, 0x3fb8aa3b, v13
	v_add_f32_e32 v17, v12, v16
	v_exp_f32_e32 v16, v13
	v_fma_f32 v13, v14, s2, -v75
	v_mul_f32_e32 v13, 0x3fb8aa3b, v13
	v_exp_f32_e32 v13, v13
	v_fma_f32 v15, v15, s2, -v75
	v_add_f32_e32 v17, v16, v17
	v_mul_f32_e32 v15, 0x3fb8aa3b, v15
	v_add_f32_e32 v14, v13, v17
	v_exp_f32_e32 v17, v15
	v_fma_f32 v8, v8, s2, -v75
	v_mul_f32_e32 v8, 0x3fb8aa3b, v8
	v_fma_f32 v9, v9, s2, -v75
	v_add_f32_e32 v15, v17, v14
	v_exp_f32_e32 v14, v8
	v_mul_f32_e32 v9, 0x3fb8aa3b, v9
	v_exp_f32_e32 v18, v9
	v_fma_f32 v9, v10, s2, -v75
	v_mul_f32_e32 v9, 0x3fb8aa3b, v9
	v_add_f32_e32 v8, v14, v15
	v_exp_f32_e32 v15, v9
	v_fma_f32 v9, v11, s2, -v75
	v_mul_f32_e32 v9, 0x3fb8aa3b, v9
	v_fma_f32 v4, v4, s2, -v75
	v_exp_f32_e32 v19, v9
	v_mul_f32_e32 v4, 0x3fb8aa3b, v4
	v_exp_f32_e32 v4, v4
	v_add_f32_e32 v8, v18, v8
	v_add_f32_e32 v8, v15, v8
	v_fma_f32 v5, v5, s2, -v75
	v_add_f32_e32 v8, v19, v8
	v_mul_f32_e32 v5, 0x3fb8aa3b, v5
	v_add_f32_e32 v9, v4, v8
	v_exp_f32_e32 v8, v5
	v_fma_f32 v5, v6, s2, -v75
	v_mul_f32_e32 v5, 0x3fb8aa3b, v5
	v_exp_f32_e32 v5, v5
	v_fma_f32 v7, v7, s2, -v75
	v_add_f32_e32 v9, v8, v9
	v_mul_f32_e32 v7, 0x3fb8aa3b, v7
	v_fma_f32 v0, v0, s2, -v75
	v_add_f32_e32 v6, v5, v9
	v_exp_f32_e32 v9, v7
	v_mul_f32_e32 v0, 0x3fb8aa3b, v0
	v_exp_f32_e32 v0, v0
	v_fma_f32 v1, v1, s2, -v75
	v_add_f32_e32 v6, v9, v6
	v_mul_f32_e32 v1, 0x3fb8aa3b, v1
	v_add_f32_e32 v7, v0, v6
	v_exp_f32_e32 v6, v1
	v_fma_f32 v1, v2, s2, -v75
	v_mul_f32_e32 v1, 0x3fb8aa3b, v1
	v_exp_f32_e32 v1, v1
	v_fma_f32 v3, v3, s2, -v75
	v_add_f32_e32 v7, v6, v7
	v_mul_f32_e32 v3, 0x3fb8aa3b, v3
	v_add_f32_e32 v2, v1, v7
	v_exp_f32_e32 v7, v3
	s_nop 0
	v_add_f32_e32 v2, v7, v2
	ds_bpermute_b32 v3, v74, v2
	s_waitcnt lgkmcnt(0)
	v_add_f32_e32 v2, v2, v3
	ds_bpermute_b32 v3, v73, v2
	s_waitcnt lgkmcnt(0)
	v_add_f32_e32 v2, v2, v3
	v_div_scale_f32 v3, s[2:3], v2, v2, 1.0
	v_rcp_f32_e32 v10, v3
	v_div_scale_f32 v11, vcc, 1.0, v2, 1.0
	s_movk_i32 s2, 0x210
	v_fma_f32 v73, -v3, v10, 1.0
	v_fmac_f32_e32 v10, v73, v10
	v_mul_f32_e32 v73, v11, v10
	v_fma_f32 v74, -v3, v73, v11
	v_fmac_f32_e32 v73, v74, v10
	v_fma_f32 v3, -v3, v73, v11
	v_div_fmas_f32 v3, v3, v10, v73
	v_div_fixup_f32 v2, v3, v2, 1.0
	v_pk_mul_f32 v[10:11], v[60:61], v[2:3] op_sel_hi:[1,0]
	v_pk_mul_f32 v[60:61], v[64:65], v[2:3] op_sel_hi:[1,0]
	v_pk_mul_f32 v[64:65], v[66:67], v[2:3] op_sel_hi:[1,0]
	v_pk_mul_f32 v[62:63], v[62:63], v[2:3] op_sel_hi:[1,0]
	v_bfe_u32 v3, v65, 16, 1
	v_bfe_u32 v66, v64, 16, 1
	v_bfe_u32 v67, v61, 16, 1
	v_bfe_u32 v73, v60, 16, 1
	v_add3_u32 v65, v65, v3, s33
	v_bfe_u32 v3, v10, 16, 1
	v_mad_u32_u24 v71, v71, s2, v72
	v_add3_u32 v73, v60, v73, s33
	v_add3_u32 v74, v61, v67, s33
	v_add3_u32 v64, v64, v66, s33
	v_bfe_u32 v60, v11, 16, 1
	v_bfe_u32 v61, v62, 16, 1
	v_bfe_u32 v66, v63, 16, 1
	v_add3_u32 v10, v10, v3, s33
	v_add_u32_e32 v3, 0x9000, v71
	v_add3_u32 v66, v63, v66, s33
	v_add3_u32 v67, v62, v61, s33
	v_add3_u32 v11, v11, v60, s33
	ds_read2_b64 v[60:63], v3 offset1:4
	v_lshrrev_b32_e32 v10, 16, v10
	v_lshrrev_b32_e32 v11, 16, v11
	v_lshrrev_b32_e32 v72, 16, v67
	v_lshrrev_b32_e32 v66, 16, v66
	v_and_or_b32 v67, v65, s29, v66
	v_and_or_b32 v66, v64, s29, v72
	v_and_or_b32 v65, v74, s29, v11
	v_and_or_b32 v64, v73, s29, v10
	v_add_u32_e32 v10, 0xb000, v71
	s_waitcnt lgkmcnt(0)
	v_mfma_f32_16x16x32_bf16 v[72:75], v[60:63], v[64:67], 0
	ds_read2_b64 v[60:63], v10 offset0:32 offset1:36
	s_waitcnt lgkmcnt(0)
	v_mfma_f32_16x16x32_bf16 v[76:79], v[60:63], v[64:67], 0
	v_add_u32_e32 v60, 0xd000, v71
	v_add_u32_e32 v61, 0xf000, v71
	ds_read2_b64 v[82:85], v60 offset0:64 offset1:68
	ds_read2_b64 v[86:89], v61 offset0:96 offset1:100
	s_waitcnt lgkmcnt(1)
	v_mfma_f32_16x16x32_bf16 v[82:85], v[82:85], v[64:67], 0
	s_waitcnt lgkmcnt(0)
	v_mfma_f32_16x16x32_bf16 v[62:65], v[86:89], v[64:67], 0
	ds_read2_b64 v[204:207], v3 offset0:8 offset1:12
	ds_read2_b64 v[208:211], v10 offset0:40 offset1:44
	ds_read2_b64 v[212:215], v60 offset0:72 offset1:76
	ds_read2_b64 v[216:219], v61 offset0:104 offset1:108
	v_mul_f32_e64 v56, v56, v2
	v_mul_f32_e64 v57, v57, v2
	v_pk_mul_f32 v[58:59], v[58:59], v[2:3] op_sel_hi:[1,0]
	v_pk_mul_f32 v[52:53], v[52:53], v[2:3] op_sel_hi:[1,0]
	v_pk_mul_f32 v[54:55], v[54:55], v[2:3] op_sel_hi:[1,0]
	v_bfe_u32 v11, v59, 16, 1
	v_bfe_u32 v66, v58, 16, 1
	v_bfe_u32 v67, v57, 16, 1
	v_bfe_u32 v71, v56, 16, 1
	v_add3_u32 v56, v56, v71, s33
	v_add3_u32 v57, v57, v67, s33
	v_add3_u32 v58, v58, v66, s33
	v_add3_u32 v11, v59, v11, s33
	v_bfe_u32 v59, v52, 16, 1
	v_bfe_u32 v66, v53, 16, 1
	v_bfe_u32 v67, v54, 16, 1
	v_bfe_u32 v71, v55, 16, 1
	v_add3_u32 v71, v55, v71, s33
	v_add3_u32 v67, v54, v67, s33
	v_add3_u32 v66, v53, v66, s33
	v_add3_u32 v59, v52, v59, s33
	v_lshrrev_b32_e32 v81, 16, v59
	v_lshrrev_b32_e32 v66, 16, v66
	v_lshrrev_b32_e32 v67, 16, v67
	v_lshrrev_b32_e32 v59, 16, v71
	v_and_or_b32 v59, v11, s29, v59
	v_and_or_b32 v58, v58, s29, v67
	v_and_or_b32 v57, v57, s29, v66
	v_and_or_b32 v56, v56, s29, v81
	s_waitcnt lgkmcnt(3)
	s_nop 1
	v_mfma_f32_16x16x32_bf16 v[52:55], v[204:207], v[56:59], v[72:75]
	s_waitcnt lgkmcnt(2)
	v_mfma_f32_16x16x32_bf16 v[72:75], v[208:211], v[56:59], v[76:79]
	s_waitcnt lgkmcnt(1)
	v_mfma_f32_16x16x32_bf16 v[76:79], v[212:215], v[56:59], v[82:85]
	s_waitcnt lgkmcnt(0)
	v_mfma_f32_16x16x32_bf16 v[56:59], v[216:219], v[56:59], v[62:65]
	ds_read2_b64 v[204:207], v3 offset0:16 offset1:20
	ds_read2_b64 v[208:211], v10 offset0:48 offset1:52
	ds_read2_b64 v[212:215], v60 offset0:80 offset1:84
	ds_read2_b64 v[216:219], v61 offset0:112 offset1:116
	v_mul_f32_e64 v48, v48, v2
	v_mul_f32_e64 v49, v49, v2
	v_pk_mul_f32 v[50:51], v[50:51], v[2:3] op_sel_hi:[1,0]
	v_pk_mul_f32 v[44:45], v[44:45], v[2:3] op_sel_hi:[1,0]
	v_pk_mul_f32 v[46:47], v[46:47], v[2:3] op_sel_hi:[1,0]
	v_bfe_u32 v11, v51, 16, 1
	v_bfe_u32 v62, v50, 16, 1
	v_bfe_u32 v63, v49, 16, 1
	v_bfe_u32 v64, v48, 16, 1
	v_add3_u32 v48, v48, v64, s33
	v_add3_u32 v49, v49, v63, s33
	v_add3_u32 v50, v50, v62, s33
	v_add3_u32 v11, v51, v11, s33
	v_bfe_u32 v51, v44, 16, 1
	v_bfe_u32 v62, v45, 16, 1
	v_bfe_u32 v63, v46, 16, 1
	v_bfe_u32 v64, v47, 16, 1
	v_add3_u32 v64, v47, v64, s33
	v_add3_u32 v63, v46, v63, s33
	v_add3_u32 v62, v45, v62, s33
	v_add3_u32 v51, v44, v51, s33
	v_lshrrev_b32_e32 v65, 16, v51
	v_lshrrev_b32_e32 v62, 16, v62
	v_lshrrev_b32_e32 v63, 16, v63
	v_lshrrev_b32_e32 v51, 16, v64
	v_and_or_b32 v51, v11, s29, v51
	v_and_or_b32 v50, v50, s29, v63
	v_and_or_b32 v49, v49, s29, v62
	v_and_or_b32 v48, v48, s29, v65
	s_waitcnt lgkmcnt(3)
	s_nop 1
	v_mfma_f32_16x16x32_bf16 v[44:47], v[204:207], v[48:51], v[52:55]
	s_waitcnt lgkmcnt(2)
	v_mfma_f32_16x16x32_bf16 v[52:55], v[208:211], v[48:51], v[72:75]
	s_waitcnt lgkmcnt(1)
	v_mfma_f32_16x16x32_bf16 v[62:65], v[212:215], v[48:51], v[76:79]
	s_waitcnt lgkmcnt(0)
	v_mfma_f32_16x16x32_bf16 v[48:51], v[216:219], v[48:51], v[56:59]
	ds_read2_b64 v[204:207], v3 offset0:24 offset1:28
	ds_read2_b64 v[208:211], v10 offset0:56 offset1:60
	ds_read2_b64 v[212:215], v60 offset0:88 offset1:92
	ds_read2_b64 v[216:219], v61 offset0:120 offset1:124
	v_mul_f32_e64 v40, v40, v2
	v_mul_f32_e64 v41, v41, v2
	v_pk_mul_f32 v[42:43], v[42:43], v[2:3] op_sel_hi:[1,0]
	v_pk_mul_f32 v[36:37], v[36:37], v[2:3] op_sel_hi:[1,0]
	v_pk_mul_f32 v[38:39], v[38:39], v[2:3] op_sel_hi:[1,0]
	v_bfe_u32 v11, v43, 16, 1
	v_bfe_u32 v56, v42, 16, 1
	v_bfe_u32 v57, v41, 16, 1
	v_bfe_u32 v58, v40, 16, 1
	v_add3_u32 v40, v40, v58, s33
	v_add3_u32 v41, v41, v57, s33
	v_add3_u32 v42, v42, v56, s33
	v_add3_u32 v11, v43, v11, s33
	v_bfe_u32 v43, v36, 16, 1
	v_bfe_u32 v56, v37, 16, 1
	v_bfe_u32 v57, v38, 16, 1
	v_bfe_u32 v58, v39, 16, 1
	v_add3_u32 v58, v39, v58, s33
	v_add3_u32 v57, v38, v57, s33
	v_add3_u32 v56, v37, v56, s33
	v_add3_u32 v43, v36, v43, s33
	v_lshrrev_b32_e32 v59, 16, v43
	v_lshrrev_b32_e32 v56, 16, v56
	v_lshrrev_b32_e32 v57, 16, v57
	v_lshrrev_b32_e32 v43, 16, v58
	v_and_or_b32 v43, v11, s29, v43
	v_and_or_b32 v42, v42, s29, v57
	v_and_or_b32 v41, v41, s29, v56
	v_and_or_b32 v40, v40, s29, v59
	s_waitcnt lgkmcnt(3)
	s_nop 1
	v_mfma_f32_16x16x32_bf16 v[36:39], v[204:207], v[40:43], v[44:47]
	s_waitcnt lgkmcnt(2)
	v_mfma_f32_16x16x32_bf16 v[44:47], v[208:211], v[40:43], v[52:55]
	s_waitcnt lgkmcnt(1)
	v_mfma_f32_16x16x32_bf16 v[52:55], v[212:215], v[40:43], v[62:65]
	s_waitcnt lgkmcnt(0)
	v_mfma_f32_16x16x32_bf16 v[40:43], v[216:219], v[40:43], v[48:51]
	ds_read2_b64 v[204:207], v3 offset0:32 offset1:36
	ds_read2_b64 v[208:211], v10 offset0:64 offset1:68
	ds_read2_b64 v[212:215], v60 offset0:96 offset1:100
	ds_read2_b64 v[216:219], v61 offset0:128 offset1:132
	v_mul_f32_e64 v32, v32, v2
	v_mul_f32_e64 v33, v33, v2
	v_pk_mul_f32 v[34:35], v[34:35], v[2:3] op_sel_hi:[1,0]
	v_pk_mul_f32 v[28:29], v[28:29], v[2:3] op_sel_hi:[1,0]
	v_pk_mul_f32 v[30:31], v[30:31], v[2:3] op_sel_hi:[1,0]
	v_bfe_u32 v11, v35, 16, 1
	v_bfe_u32 v48, v34, 16, 1
	v_bfe_u32 v49, v33, 16, 1
	v_bfe_u32 v50, v32, 16, 1
	v_add3_u32 v32, v32, v50, s33
	v_add3_u32 v33, v33, v49, s33
	v_add3_u32 v34, v34, v48, s33
	v_add3_u32 v11, v35, v11, s33
	v_bfe_u32 v35, v28, 16, 1
	v_bfe_u32 v48, v29, 16, 1
	v_bfe_u32 v49, v30, 16, 1
	v_bfe_u32 v50, v31, 16, 1
	v_add3_u32 v50, v31, v50, s33
	v_add3_u32 v49, v30, v49, s33
	v_add3_u32 v48, v29, v48, s33
	v_add3_u32 v35, v28, v35, s33
	v_lshrrev_b32_e32 v51, 16, v35
	v_lshrrev_b32_e32 v48, 16, v48
	v_lshrrev_b32_e32 v49, 16, v49
	v_lshrrev_b32_e32 v35, 16, v50
	v_and_or_b32 v35, v11, s29, v35
	v_and_or_b32 v34, v34, s29, v49
	v_and_or_b32 v33, v33, s29, v48
	v_and_or_b32 v32, v32, s29, v51
	s_waitcnt lgkmcnt(3)
	s_nop 1
	v_mfma_f32_16x16x32_bf16 v[28:31], v[204:207], v[32:35], v[36:39]
	s_waitcnt lgkmcnt(2)
	v_mfma_f32_16x16x32_bf16 v[36:39], v[208:211], v[32:35], v[44:47]
	s_waitcnt lgkmcnt(1)
	v_mfma_f32_16x16x32_bf16 v[44:47], v[212:215], v[32:35], v[52:55]
	s_waitcnt lgkmcnt(0)
	v_mfma_f32_16x16x32_bf16 v[32:35], v[216:219], v[32:35], v[40:43]
	ds_read2_b64 v[204:207], v3 offset0:40 offset1:44
	ds_read2_b64 v[208:211], v10 offset0:72 offset1:76
	ds_read2_b64 v[212:215], v60 offset0:104 offset1:108
	ds_read2_b64 v[216:219], v61 offset0:136 offset1:140
	v_mul_f32_e64 v24, v24, v2
	v_mul_f32_e64 v25, v25, v2
	v_pk_mul_f32 v[26:27], v[26:27], v[2:3] op_sel_hi:[1,0]
	v_pk_mul_f32 v[20:21], v[20:21], v[2:3] op_sel_hi:[1,0]
	v_pk_mul_f32 v[22:23], v[22:23], v[2:3] op_sel_hi:[1,0]
	v_bfe_u32 v11, v27, 16, 1
	v_bfe_u32 v40, v26, 16, 1
	v_bfe_u32 v41, v25, 16, 1
	v_bfe_u32 v42, v24, 16, 1
	v_add3_u32 v24, v24, v42, s33
	v_add3_u32 v25, v25, v41, s33
	v_add3_u32 v26, v26, v40, s33
	v_add3_u32 v11, v27, v11, s33
	v_bfe_u32 v27, v20, 16, 1
	v_bfe_u32 v40, v21, 16, 1
	v_bfe_u32 v41, v22, 16, 1
	v_bfe_u32 v42, v23, 16, 1
	v_add3_u32 v42, v23, v42, s33
	v_add3_u32 v41, v22, v41, s33
	v_add3_u32 v40, v21, v40, s33
	v_add3_u32 v27, v20, v27, s33
	v_lshrrev_b32_e32 v43, 16, v27
	v_lshrrev_b32_e32 v40, 16, v40
	v_lshrrev_b32_e32 v41, 16, v41
	v_lshrrev_b32_e32 v27, 16, v42
	v_and_or_b32 v27, v11, s29, v27
	v_and_or_b32 v26, v26, s29, v41
	v_and_or_b32 v25, v25, s29, v40
	v_and_or_b32 v24, v24, s29, v43
	s_waitcnt lgkmcnt(3)
	s_nop 1
	v_mfma_f32_16x16x32_bf16 v[20:23], v[204:207], v[24:27], v[28:31]
	s_waitcnt lgkmcnt(2)
	v_mfma_f32_16x16x32_bf16 v[28:31], v[208:211], v[24:27], v[36:39]
	s_waitcnt lgkmcnt(1)
	v_mfma_f32_16x16x32_bf16 v[36:39], v[212:215], v[24:27], v[44:47]
	s_waitcnt lgkmcnt(0)
	v_mfma_f32_16x16x32_bf16 v[24:27], v[216:219], v[24:27], v[32:35]
	ds_read2_b64 v[204:207], v3 offset0:48 offset1:52
	ds_read2_b64 v[208:211], v10 offset0:80 offset1:84
	ds_read2_b64 v[212:215], v60 offset0:112 offset1:116
	ds_read2_b64 v[216:219], v61 offset0:144 offset1:148
	v_mul_f32_e64 v16, v16, v2
	v_mul_f32_e64 v17, v17, v2
	v_pk_mul_f32 v[18:19], v[18:19], v[2:3] op_sel_hi:[1,0]
	v_pk_mul_f32 v[12:13], v[12:13], v[2:3] op_sel_hi:[1,0]
	v_pk_mul_f32 v[14:15], v[14:15], v[2:3] op_sel_hi:[1,0]
	v_bfe_u32 v11, v19, 16, 1
	v_bfe_u32 v32, v18, 16, 1
	v_bfe_u32 v33, v17, 16, 1
	v_bfe_u32 v34, v16, 16, 1
	v_add3_u32 v16, v16, v34, s33
	v_add3_u32 v17, v17, v33, s33
	v_add3_u32 v18, v18, v32, s33
	v_add3_u32 v11, v19, v11, s33
	v_bfe_u32 v19, v12, 16, 1
	v_bfe_u32 v32, v13, 16, 1
	v_bfe_u32 v33, v14, 16, 1
	v_bfe_u32 v34, v15, 16, 1
	v_add3_u32 v34, v15, v34, s33
	v_add3_u32 v33, v14, v33, s33
	v_add3_u32 v32, v13, v32, s33
	v_add3_u32 v19, v12, v19, s33
	v_lshrrev_b32_e32 v35, 16, v19
	v_lshrrev_b32_e32 v32, 16, v32
	v_lshrrev_b32_e32 v33, 16, v33
	v_lshrrev_b32_e32 v19, 16, v34
	v_and_or_b32 v19, v11, s29, v19
	v_and_or_b32 v18, v18, s29, v33
	v_and_or_b32 v17, v17, s29, v32
	v_and_or_b32 v16, v16, s29, v35
	s_waitcnt lgkmcnt(3)
	s_nop 1
	v_mfma_f32_16x16x32_bf16 v[12:15], v[204:207], v[16:19], v[20:23]
	s_waitcnt lgkmcnt(2)
	v_mfma_f32_16x16x32_bf16 v[20:23], v[208:211], v[16:19], v[28:31]
	s_waitcnt lgkmcnt(1)
	v_mfma_f32_16x16x32_bf16 v[28:31], v[212:215], v[16:19], v[36:39]
	s_waitcnt lgkmcnt(0)
	v_mfma_f32_16x16x32_bf16 v[16:19], v[216:219], v[16:19], v[24:27]
	ds_read2_b64 v[204:207], v3 offset0:56 offset1:60
	ds_read2_b64 v[208:211], v10 offset0:88 offset1:92
	ds_read2_b64 v[212:215], v60 offset0:120 offset1:124
	ds_read2_b64 v[216:219], v61 offset0:152 offset1:156
	v_mul_f32_e64 v8, v8, v2
	v_mul_f32_e64 v9, v9, v2
	v_pk_mul_f32 v[6:7], v[6:7], v[2:3] op_sel_hi:[1,0]
	v_pk_mul_f32 v[4:5], v[4:5], v[2:3] op_sel_hi:[1,0]
	v_pk_mul_f32 v[0:1], v[0:1], v[2:3] op_sel_hi:[1,0]
	v_bfe_u32 v2, v7, 16, 1
	v_bfe_u32 v24, v9, 16, 1
	v_bfe_u32 v25, v8, 16, 1
	v_add3_u32 v8, v8, v25, s33
	v_add3_u32 v9, v9, v24, s33
	v_add3_u32 v7, v7, v2, s33
	v_bfe_u32 v2, v4, 16, 1
	v_bfe_u32 v24, v0, 16, 1
	v_bfe_u32 v25, v1, 16, 1
	v_add3_u32 v25, v1, v25, s33
	v_add3_u32 v24, v0, v24, s33
	v_add3_u32 v4, v4, v2, s33
	v_bfe_u32 v11, v6, 16, 1
	v_add3_u32 v6, v6, v11, s33
	v_bfe_u32 v11, v5, 16, 1
	v_add3_u32 v5, v5, v11, s33
	v_lshrrev_b32_e32 v4, 16, v4
	v_lshrrev_b32_e32 v5, 16, v5
	v_lshrrev_b32_e32 v11, 16, v24
	v_lshrrev_b32_e32 v24, 16, v25
	v_and_or_b32 v27, v7, s29, v24
	v_and_or_b32 v26, v6, s29, v11
	v_and_or_b32 v25, v9, s29, v5
	v_and_or_b32 v24, v8, s29, v4
	s_waitcnt lgkmcnt(3)
	s_nop 1
	v_mfma_f32_16x16x32_bf16 v[12:15], v[204:207], v[24:27], v[12:15]
	s_waitcnt lgkmcnt(2)
	v_mfma_f32_16x16x32_bf16 v[8:11], v[208:211], v[24:27], v[20:23]
	s_waitcnt lgkmcnt(1)
	v_mfma_f32_16x16x32_bf16 v[4:7], v[212:215], v[24:27], v[28:31]
	s_waitcnt lgkmcnt(0)
	v_mfma_f32_16x16x32_bf16 v[0:3], v[216:219], v[24:27], v[16:19]
	s_and_b64 exec, exec, s[0:1]
	s_cbranch_execz .LBB0_91
	s_lshl_b32 s0, s10, 11
	v_bfe_u32 v18, v12, 16, 1
	s_add_u32 s0, s6, s0
	v_add3_u32 v12, v12, v18, s33
	v_bfe_u32 v18, v13, 16, 1
	s_addc_u32 s1, s7, 0
	v_add3_u32 v13, v13, v18, s33
	v_lshrrev_b32_e32 v12, 16, v12
	s_add_u32 s0, s0, s11
	v_and_or_b32 v12, v13, s29, v12
	v_bfe_u32 v13, v14, 16, 1
	s_addc_u32 s1, s1, 0
	v_lshlrev_b64 v[16:17], 11, v[68:69]
	v_add3_u32 v13, v14, v13, s33
	v_bfe_u32 v14, v15, 16, 1
	v_lshl_add_u64 v[16:17], s[0:1], 0, v[16:17]
	v_mov_b32_e32 v71, v80
	v_add3_u32 v14, v15, v14, s33
	v_lshrrev_b32_e32 v13, 16, v13
	v_lshl_add_u64 v[16:17], v[16:17], 0, v[70:71]
	v_and_or_b32 v13, v14, s29, v13
	global_store_dwordx2 v[16:17], v[12:13], off offset:1536
	v_bfe_u32 v12, v8, 16, 1
	v_add3_u32 v8, v8, v12, s33
	v_bfe_u32 v12, v9, 16, 1
	v_add3_u32 v9, v9, v12, s33
	v_lshrrev_b32_e32 v8, 16, v8
	v_and_or_b32 v8, v9, s29, v8
	v_bfe_u32 v9, v10, 16, 1
	v_add3_u32 v9, v10, v9, s33
	v_bfe_u32 v10, v11, 16, 1
	v_add3_u32 v10, v11, v10, s33
	v_lshrrev_b32_e32 v9, 16, v9
	v_and_or_b32 v9, v10, s29, v9
	global_store_dwordx2 v[16:17], v[8:9], off offset:1568
	v_bfe_u32 v8, v4, 16, 1
	v_add3_u32 v4, v4, v8, s33
	v_bfe_u32 v8, v5, 16, 1
	v_add3_u32 v5, v5, v8, s33
	v_lshrrev_b32_e32 v4, 16, v4
	v_and_or_b32 v4, v5, s29, v4
	v_bfe_u32 v5, v6, 16, 1
	v_add3_u32 v5, v6, v5, s33
	v_bfe_u32 v6, v7, 16, 1
	v_add3_u32 v6, v7, v6, s33
	v_lshrrev_b32_e32 v5, 16, v5
	v_and_or_b32 v5, v6, s29, v5
	global_store_dwordx2 v[16:17], v[4:5], off offset:1600
	v_bfe_u32 v4, v0, 16, 1
	v_add3_u32 v0, v0, v4, s33
	v_bfe_u32 v4, v1, 16, 1
	v_add3_u32 v1, v1, v4, s33
	v_lshrrev_b32_e32 v0, 16, v0
	v_and_or_b32 v0, v1, s29, v0
	v_bfe_u32 v1, v2, 16, 1
	v_add3_u32 v1, v2, v1, s33
	v_bfe_u32 v2, v3, 16, 1
	v_add3_u32 v2, v3, v2, s33
	v_lshrrev_b32_e32 v1, 16, v1
	v_and_or_b32 v1, v2, s29, v1
	global_store_dwordx2 v[16:17], v[0:1], off offset:1632
